# UP/WIN/DN-OUT GEMM units: first K-loop iteration peeled, its k=0 MFMAs start from srcC=0; the 128 v_mov accumulator zeroing per unit removed
# speedup vs baseline: 1.0077x; 1.0077x over previous
.LBB0_402:
	s_cmp_eq_u32 s56, 4
	s_cselect_b32 s60, 19, s56
	s_cmp_eq_u32 s56, 5
	s_cselect_b32 s60, 4, s60
	s_cmp_eq_u32 s56, 10
	s_cselect_b32 s60, 5, s60
	s_cmp_eq_u32 s56, 19
	s_cselect_b32 s56, 10, s60
	s_ashr_i32 s59, s58, 31
	s_lshl_b64 s[60:61], s[58:59], 19
	s_add_u32 s60, s14, s60
	s_addc_u32 s61, s15, s61
	s_and_b64 s[62:63], s[36:37], exec
	s_cselect_b32 s59, s61, s67
	s_cselect_b32 s70, s60, s66
	s_ashr_i32 s57, s56, 31
	s_lshl_b64 s[62:63], s[56:57], 19
	s_add_u32 s62, s2, s62
	s_addc_u32 s63, s3, s63
	s_and_b64 s[68:69], s[36:37], exec
	s_cselect_b32 s57, s63, s65
	s_cselect_b32 s71, s62, s64
	s_add_u32 s72, s64, 0x100
	s_addc_u32 s73, s65, 0
	s_add_u32 s64, s66, 0x40080
	s_addc_u32 s65, s67, 0
	s_mov_b32 s74, -2
	s_cmp_eq_u32 s78, 19
	s_cselect_b32 vcc_hi, 1, 0
	v_readlane_b32 vcc_lo, v252, 19
	s_and_b32 vcc_lo, vcc_lo, 0xc0
	s_cmp_lg_u32 vcc_lo, 0
	s_cselect_b32 vcc_lo, vcc_hi, 0
	s_add_u32 s66, s64, 0xfffc0080
	s_addc_u32 s67, s65, -1
	s_add_i32 s75, 0, 0x10000
	s_cmp_eq_u32 s74, 12
	s_cselect_b32 s69, s59, s67
	s_cselect_b32 s68, s70, s66
	v_add_u32_e32 v0, s75, v169
	s_cselect_b32 s67, s57, s73
	s_cselect_b32 s66, s71, s72
	s_add_i32 s79, 0, 0x14000
	ds_read_b128 v[134:137], v0
	ds_read_b128 v[138:141], v0 offset:1024
	ds_read_b128 v[142:145], v0 offset:2048
	ds_read_b128 v[146:149], v0 offset:3072
	v_add_u32_e32 v0, s79, v169
	ds_read_b128 v[150:153], v0
	ds_read_b128 v[154:157], v0 offset:1024
	ds_read_b128 v[158:161], v0 offset:2048
	ds_read_b128 v[162:165], v0 offset:3072
	s_add_i32 m0, s9, 0xc000
	ds_read_b128 v[182:185], v171
	ds_read_b128 v[186:189], v171 offset:1024
	ds_read_b128 v[190:193], v171 offset:2048
	ds_read_b128 v[194:197], v171 offset:3072
	ds_read_b128 v[208:211], v171 offset:4096
	ds_read_b128 v[212:215], v171 offset:5120
	ds_read_b128 v[216:219], v171 offset:6144
	ds_read_b128 v[232:235], v171 offset:7168
	global_load_lds_dwordx4 v180, s[64:65]
	s_add_i32 m0, s9, 0xe000
	s_nop 0
	global_load_lds_dwordx4 v178, s[64:65]
	s_waitcnt vmcnt(8)
	s_waitcnt lgkmcnt(0)
	s_barrier
	s_setprio 1
	s_waitcnt lgkmcnt(0)
	s_cmp_lg_u32 vcc_lo, 0
	s_cbranch_scc1 .Lwinskip_0_pl
	v_mfma_f32_16x16x32_bf16 v[130:133], v[134:137], v[182:185], 0
	v_mfma_f32_16x16x32_bf16 v[126:129], v[142:145], v[182:185], 0
	v_mfma_f32_16x16x32_bf16 v[122:125], v[134:137], v[190:193], 0
	v_mfma_f32_16x16x32_bf16 v[118:121], v[142:145], v[190:193], 0
	v_mfma_f32_16x16x32_bf16 v[114:117], v[134:137], v[208:211], 0
	v_mfma_f32_16x16x32_bf16 v[110:113], v[142:145], v[208:211], 0
	v_mfma_f32_16x16x32_bf16 v[106:109], v[134:137], v[216:219], 0
	v_mfma_f32_16x16x32_bf16 v[102:105], v[142:145], v[216:219], 0
	v_mfma_f32_16x16x32_bf16 v[130:133], v[138:141], v[186:189], v[130:133]
	v_mfma_f32_16x16x32_bf16 v[126:129], v[146:149], v[186:189], v[126:129]
	v_mfma_f32_16x16x32_bf16 v[122:125], v[138:141], v[194:197], v[122:125]
	v_mfma_f32_16x16x32_bf16 v[118:121], v[146:149], v[194:197], v[118:121]
	v_mfma_f32_16x16x32_bf16 v[114:117], v[138:141], v[212:215], v[114:117]
	v_mfma_f32_16x16x32_bf16 v[110:113], v[146:149], v[212:215], v[110:113]
	v_mfma_f32_16x16x32_bf16 v[106:109], v[138:141], v[232:235], v[106:109]
	v_mfma_f32_16x16x32_bf16 v[102:105], v[146:149], v[232:235], v[102:105]
.Lwinskip_0_pl:
	s_setprio 0
	s_setprio 1
	s_cmp_lg_u32 vcc_hi, 0
	s_cbranch_scc1 .Lwinskip_1_pl
	v_mfma_f32_16x16x32_bf16 v[62:65], v[150:153], v[182:185], 0
	v_mfma_f32_16x16x32_bf16 v[58:61], v[158:161], v[182:185], 0
	v_mfma_f32_16x16x32_bf16 v[54:57], v[150:153], v[190:193], 0
	v_mfma_f32_16x16x32_bf16 v[50:53], v[158:161], v[190:193], 0
	v_mfma_f32_16x16x32_bf16 v[46:49], v[150:153], v[208:211], 0
	v_mfma_f32_16x16x32_bf16 v[42:45], v[158:161], v[208:211], 0
	v_mfma_f32_16x16x32_bf16 v[38:41], v[150:153], v[216:219], 0
	v_mfma_f32_16x16x32_bf16 v[34:37], v[158:161], v[216:219], 0
	v_mfma_f32_16x16x32_bf16 v[62:65], v[154:157], v[186:189], v[62:65]
	v_mfma_f32_16x16x32_bf16 v[58:61], v[162:165], v[186:189], v[58:61]
	v_mfma_f32_16x16x32_bf16 v[54:57], v[154:157], v[194:197], v[54:57]
	v_mfma_f32_16x16x32_bf16 v[50:53], v[162:165], v[194:197], v[50:53]
	v_mfma_f32_16x16x32_bf16 v[46:49], v[154:157], v[212:215], v[46:49]
	v_mfma_f32_16x16x32_bf16 v[42:45], v[162:165], v[212:215], v[42:45]
	v_mfma_f32_16x16x32_bf16 v[38:41], v[154:157], v[232:235], v[38:41]
	v_mfma_f32_16x16x32_bf16 v[34:37], v[162:165], v[232:235], v[34:37]
.Lwinskip_1_pl:
	s_setprio 0
	s_barrier
	s_add_i32 s75, s75, s8
	s_mov_b32 m0, s75
	ds_read_b128 v[182:185], v171 offset:16384
	ds_read_b128 v[186:189], v171 offset:17408
	ds_read_b128 v[190:193], v171 offset:18432
	ds_read_b128 v[194:197], v171 offset:19456
	ds_read_b128 v[208:211], v171 offset:20480
	ds_read_b128 v[212:215], v171 offset:21504
	ds_read_b128 v[216:219], v171 offset:22528
	ds_read_b128 v[232:235], v171 offset:23552
	global_load_lds_dwordx4 v166, s[66:67]
	s_add_i32 m0, s75, 0x2000
	s_add_u32 s76, s66, 0x40000
	s_addc_u32 s77, s67, 0
	s_add_i32 s75, s79, s8
	global_load_lds_dwordx4 v94, s[66:67]
	s_mov_b32 m0, s75
	s_nop 0
	global_load_lds_dwordx4 v166, s[76:77]
	s_add_i32 m0, s75, 0x2000
	s_nop 0
	global_load_lds_dwordx4 v94, s[76:77]
	s_mov_b32 m0, s9
	s_nop 0
	global_load_lds_dwordx4 v166, s[68:69]
	s_mov_b32 m0, s12
	s_nop 0
	global_load_lds_dwordx4 v94, s[68:69]
	s_waitcnt vmcnt(8)
	s_waitcnt lgkmcnt(0)
	s_barrier
	s_setprio 1
	s_waitcnt lgkmcnt(0)
	s_cmp_lg_u32 vcc_lo, 0
	s_cbranch_scc1 .Lwinskip_2_pl
	v_mfma_f32_16x16x32_bf16 v[98:101], v[134:137], v[182:185], 0
	v_mfma_f32_16x16x32_bf16 v[90:93], v[142:145], v[182:185], 0
	v_mfma_f32_16x16x32_bf16 v[86:89], v[134:137], v[190:193], 0
	v_mfma_f32_16x16x32_bf16 v[82:85], v[142:145], v[190:193], 0
	v_mfma_f32_16x16x32_bf16 v[78:81], v[134:137], v[208:211], 0
	v_mfma_f32_16x16x32_bf16 v[74:77], v[142:145], v[208:211], 0
	v_mfma_f32_16x16x32_bf16 v[70:73], v[134:137], v[216:219], 0
	v_mfma_f32_16x16x32_bf16 v[66:69], v[142:145], v[216:219], 0
	v_mfma_f32_16x16x32_bf16 v[98:101], v[138:141], v[186:189], v[98:101]
	v_mfma_f32_16x16x32_bf16 v[90:93], v[146:149], v[186:189], v[90:93]
	v_mfma_f32_16x16x32_bf16 v[86:89], v[138:141], v[194:197], v[86:89]
	v_mfma_f32_16x16x32_bf16 v[82:85], v[146:149], v[194:197], v[82:85]
	v_mfma_f32_16x16x32_bf16 v[78:81], v[138:141], v[212:215], v[78:81]
	v_mfma_f32_16x16x32_bf16 v[74:77], v[146:149], v[212:215], v[74:77]
	v_mfma_f32_16x16x32_bf16 v[70:73], v[138:141], v[232:235], v[70:73]
	v_mfma_f32_16x16x32_bf16 v[66:69], v[146:149], v[232:235], v[66:69]
.Lwinskip_2_pl:
	s_setprio 0
	s_setprio 1
	s_cmp_lg_u32 vcc_hi, 0
	s_cbranch_scc1 .Lwinskip_3_pl
	v_mfma_f32_16x16x32_bf16 v[30:33], v[150:153], v[182:185], 0
	v_mfma_f32_16x16x32_bf16 v[26:29], v[158:161], v[182:185], 0
	v_mfma_f32_16x16x32_bf16 v[22:25], v[150:153], v[190:193], 0
	v_mfma_f32_16x16x32_bf16 v[18:21], v[158:161], v[190:193], 0
	v_mfma_f32_16x16x32_bf16 v[14:17], v[150:153], v[208:211], 0
	v_mfma_f32_16x16x32_bf16 v[10:13], v[158:161], v[208:211], 0
	v_mfma_f32_16x16x32_bf16 v[6:9], v[150:153], v[216:219], 0
	v_mfma_f32_16x16x32_bf16 v[2:5], v[158:161], v[216:219], 0
	v_mfma_f32_16x16x32_bf16 v[30:33], v[154:157], v[186:189], v[30:33]
	v_mfma_f32_16x16x32_bf16 v[26:29], v[162:165], v[186:189], v[26:29]
	v_mfma_f32_16x16x32_bf16 v[22:25], v[154:157], v[194:197], v[22:25]
	v_mfma_f32_16x16x32_bf16 v[18:21], v[162:165], v[194:197], v[18:21]
	v_mfma_f32_16x16x32_bf16 v[14:17], v[154:157], v[212:215], v[14:17]
	v_mfma_f32_16x16x32_bf16 v[10:13], v[162:165], v[212:215], v[10:13]
	v_mfma_f32_16x16x32_bf16 v[6:9], v[154:157], v[232:235], v[6:9]
	v_mfma_f32_16x16x32_bf16 v[2:5], v[162:165], v[232:235], v[2:5]

.Lwinskip_7_pl:
	s_setprio 0
	s_barrier
	s_add_i32 s74, s74, 2
	s_add_u32 s72, s72, 0x100
	s_addc_u32 s73, s73, 0
	s_add_u32 s64, s64, 0x100
	s_addc_u32 s65, s65, 0
.LBB0_403:
	s_cmp_eq_u32 s78, 19
	s_cselect_b32 vcc_hi, 1, 0
	v_readlane_b32 vcc_lo, v252, 19
	s_and_b32 vcc_lo, vcc_lo, 0xc0
	s_cmp_lg_u32 vcc_lo, 0
	s_cselect_b32 vcc_lo, vcc_hi, 0
	s_add_u32 s66, s64, 0xfffc0080
	s_addc_u32 s67, s65, -1
	s_add_i32 s75, 0, 0x10000
	s_cmp_eq_u32 s74, 12
	s_cselect_b32 s69, s59, s67
	s_cselect_b32 s68, s70, s66
	v_add_u32_e32 v0, s75, v169
	s_cselect_b32 s67, s57, s73
	s_cselect_b32 s66, s71, s72
	s_add_i32 s79, 0, 0x14000
	ds_read_b128 v[134:137], v0
	ds_read_b128 v[138:141], v0 offset:1024
	ds_read_b128 v[142:145], v0 offset:2048
	ds_read_b128 v[146:149], v0 offset:3072
	v_add_u32_e32 v0, s79, v169
	ds_read_b128 v[150:153], v0
	ds_read_b128 v[154:157], v0 offset:1024
	ds_read_b128 v[158:161], v0 offset:2048
	ds_read_b128 v[162:165], v0 offset:3072
	s_add_i32 m0, s9, 0xc000
	ds_read_b128 v[182:185], v171
	ds_read_b128 v[186:189], v171 offset:1024
	ds_read_b128 v[190:193], v171 offset:2048
	ds_read_b128 v[194:197], v171 offset:3072
	ds_read_b128 v[208:211], v171 offset:4096
	ds_read_b128 v[212:215], v171 offset:5120
	ds_read_b128 v[216:219], v171 offset:6144
	ds_read_b128 v[232:235], v171 offset:7168
	global_load_lds_dwordx4 v180, s[64:65]
	s_add_i32 m0, s9, 0xe000
	s_nop 0
	global_load_lds_dwordx4 v178, s[64:65]
	s_waitcnt vmcnt(8)
	s_waitcnt lgkmcnt(0)
	s_barrier
	s_setprio 1
	s_waitcnt lgkmcnt(0)
	s_cmp_lg_u32 vcc_lo, 0
	s_cbranch_scc1 .Lwinskip_0
	v_mfma_f32_16x16x32_bf16 v[130:133], v[134:137], v[182:185], v[130:133]
	v_mfma_f32_16x16x32_bf16 v[126:129], v[142:145], v[182:185], v[126:129]
	v_mfma_f32_16x16x32_bf16 v[122:125], v[134:137], v[190:193], v[122:125]
	v_mfma_f32_16x16x32_bf16 v[118:121], v[142:145], v[190:193], v[118:121]
	v_mfma_f32_16x16x32_bf16 v[114:117], v[134:137], v[208:211], v[114:117]
	v_mfma_f32_16x16x32_bf16 v[110:113], v[142:145], v[208:211], v[110:113]
	v_mfma_f32_16x16x32_bf16 v[106:109], v[134:137], v[216:219], v[106:109]
	v_mfma_f32_16x16x32_bf16 v[102:105], v[142:145], v[216:219], v[102:105]
	v_mfma_f32_16x16x32_bf16 v[130:133], v[138:141], v[186:189], v[130:133]
	v_mfma_f32_16x16x32_bf16 v[126:129], v[146:149], v[186:189], v[126:129]
	v_mfma_f32_16x16x32_bf16 v[122:125], v[138:141], v[194:197], v[122:125]
	v_mfma_f32_16x16x32_bf16 v[118:121], v[146:149], v[194:197], v[118:121]
	v_mfma_f32_16x16x32_bf16 v[114:117], v[138:141], v[212:215], v[114:117]
	v_mfma_f32_16x16x32_bf16 v[110:113], v[146:149], v[212:215], v[110:113]
	v_mfma_f32_16x16x32_bf16 v[106:109], v[138:141], v[232:235], v[106:109]
	v_mfma_f32_16x16x32_bf16 v[102:105], v[146:149], v[232:235], v[102:105]

.LBB0_527:
	s_add_u32 s51, s22, 0x100
	s_addc_u32 s52, s23, 0
	s_add_u32 s22, s30, 0x80
	s_addc_u32 s23, s31, 0
	s_mov_b32 s30, 0
	s_waitcnt lgkmcnt(0)
	s_add_i32 s53, s30, 2
	s_add_u32 s54, s22, 0x80
	s_addc_u32 s31, s23, 0
	s_add_i32 s56, 0, 0x10000
	s_cmp_eq_u32 s46, s30
	s_cselect_b32 s31, s1, s31
	s_cselect_b32 s30, s0, s54
	s_cselect_b32 s55, s21, s52
	s_cselect_b32 s54, s20, s51
	s_add_i32 s57, 0, 0x14000
	v_add_u32_e32 v152, s56, v232
	v_add_u32_e32 v168, s57, v232
	ds_read_b128 v[140:143], v152
	ds_read_b128 v[144:147], v152 offset:1024
	ds_read_b128 v[148:151], v152 offset:2048
	ds_read_b128 v[152:155], v152 offset:3072
	ds_read_b128 v[156:159], v168
	ds_read_b128 v[160:163], v168 offset:1024
	ds_read_b128 v[164:167], v168 offset:2048
	ds_read_b128 v[168:171], v168 offset:3072
	s_add_i32 m0, s28, 0xc000
	ds_read_b128 v[172:175], v236
	ds_read_b128 v[176:179], v236 offset:1024
	ds_read_b128 v[180:183], v236 offset:2048
	ds_read_b128 v[184:187], v236 offset:3072
	ds_read_b128 v[188:191], v236 offset:4096
	ds_read_b128 v[192:195], v236 offset:5120
	ds_read_b128 v[208:211], v236 offset:6144
	ds_read_b128 v[212:215], v236 offset:7168
	global_load_lds_dwordx4 v138, s[22:23]
	s_add_i32 m0, s28, 0xe000
	s_nop 0
	global_load_lds_dwordx4 v136, s[22:23]
	s_waitcnt vmcnt(8)
	s_waitcnt lgkmcnt(0)
	s_barrier
	s_setprio 1
	s_waitcnt lgkmcnt(0)
	v_mfma_f32_16x16x32_bf16 v[130:133], v[140:143], v[172:175], 0
	v_mfma_f32_16x16x32_bf16 v[126:129], v[148:151], v[172:175], 0
	v_mfma_f32_16x16x32_bf16 v[114:117], v[140:143], v[180:183], 0
	v_mfma_f32_16x16x32_bf16 v[110:113], v[148:151], v[180:183], 0
	v_mfma_f32_16x16x32_bf16 v[98:101], v[140:143], v[188:191], 0
	v_mfma_f32_16x16x32_bf16 v[90:93], v[148:151], v[188:191], 0
	v_mfma_f32_16x16x32_bf16 v[78:81], v[140:143], v[208:211], 0
	v_mfma_f32_16x16x32_bf16 v[74:77], v[148:151], v[208:211], 0
	v_mfma_f32_16x16x32_bf16 v[130:133], v[144:147], v[176:179], v[130:133]
	v_mfma_f32_16x16x32_bf16 v[126:129], v[152:155], v[176:179], v[126:129]
	v_mfma_f32_16x16x32_bf16 v[114:117], v[144:147], v[184:187], v[114:117]
	v_mfma_f32_16x16x32_bf16 v[110:113], v[152:155], v[184:187], v[110:113]
	v_mfma_f32_16x16x32_bf16 v[98:101], v[144:147], v[192:195], v[98:101]
	v_mfma_f32_16x16x32_bf16 v[90:93], v[152:155], v[192:195], v[90:93]
	v_mfma_f32_16x16x32_bf16 v[78:81], v[144:147], v[212:215], v[78:81]
	v_mfma_f32_16x16x32_bf16 v[74:77], v[152:155], v[212:215], v[74:77]
	s_setprio 0
	s_setprio 1
	v_mfma_f32_16x16x32_bf16 v[122:125], v[156:159], v[172:175], 0
	v_mfma_f32_16x16x32_bf16 v[118:121], v[164:167], v[172:175], 0
	v_mfma_f32_16x16x32_bf16 v[106:109], v[156:159], v[180:183], 0
	v_mfma_f32_16x16x32_bf16 v[102:105], v[164:167], v[180:183], 0
	v_mfma_f32_16x16x32_bf16 v[86:89], v[156:159], v[188:191], 0
	v_mfma_f32_16x16x32_bf16 v[82:85], v[164:167], v[188:191], 0
	v_mfma_f32_16x16x32_bf16 v[70:73], v[156:159], v[208:211], 0
	v_mfma_f32_16x16x32_bf16 v[66:69], v[164:167], v[208:211], 0
	v_mfma_f32_16x16x32_bf16 v[122:125], v[160:163], v[176:179], v[122:125]
	v_mfma_f32_16x16x32_bf16 v[118:121], v[168:171], v[176:179], v[118:121]
	v_mfma_f32_16x16x32_bf16 v[106:109], v[160:163], v[184:187], v[106:109]
	v_mfma_f32_16x16x32_bf16 v[102:105], v[168:171], v[184:187], v[102:105]
	v_mfma_f32_16x16x32_bf16 v[86:89], v[160:163], v[192:195], v[86:89]
	v_mfma_f32_16x16x32_bf16 v[82:85], v[168:171], v[192:195], v[82:85]
	v_mfma_f32_16x16x32_bf16 v[70:73], v[160:163], v[212:215], v[70:73]
	v_mfma_f32_16x16x32_bf16 v[66:69], v[168:171], v[212:215], v[66:69]
	s_setprio 0
	s_barrier
	s_add_i32 s56, s56, s25
	s_mov_b32 m0, s56
	ds_read_b128 v[172:175], v236 offset:16384
	ds_read_b128 v[176:179], v236 offset:17408
	ds_read_b128 v[180:183], v236 offset:18432
	ds_read_b128 v[184:187], v236 offset:19456
	ds_read_b128 v[188:191], v236 offset:20480
	ds_read_b128 v[192:195], v236 offset:21504
	ds_read_b128 v[208:211], v236 offset:22528
	ds_read_b128 v[212:215], v236 offset:23552
	global_load_lds_dwordx4 v0, s[54:55]
	s_add_i32 m0, s56, 0x2000
	s_nop 0
	global_load_lds_dwordx4 v94, s[54:55]
	s_add_u32 s54, s54, s6
	s_addc_u32 s55, s55, 0
	s_add_i32 s56, s57, s25
	s_mov_b32 m0, s56
	s_nop 0
	global_load_lds_dwordx4 v0, s[54:55]
	s_add_i32 m0, s56, 0x2000
	s_nop 0
	global_load_lds_dwordx4 v94, s[54:55]
	s_mov_b32 m0, s28
	s_nop 0
	global_load_lds_dwordx4 v0, s[30:31]
	s_mov_b32 m0, s29
	s_nop 0
	global_load_lds_dwordx4 v94, s[30:31]
	s_waitcnt vmcnt(8)
	s_waitcnt lgkmcnt(0)
	s_barrier
	s_setprio 1
	s_waitcnt lgkmcnt(0)
	v_mfma_f32_16x16x32_bf16 v[62:65], v[140:143], v[172:175], 0
	v_mfma_f32_16x16x32_bf16 v[58:61], v[148:151], v[172:175], 0
	v_mfma_f32_16x16x32_bf16 v[46:49], v[140:143], v[180:183], 0
	v_mfma_f32_16x16x32_bf16 v[42:45], v[148:151], v[180:183], 0
	v_mfma_f32_16x16x32_bf16 v[30:33], v[140:143], v[188:191], 0
	v_mfma_f32_16x16x32_bf16 v[26:29], v[148:151], v[188:191], 0
	v_mfma_f32_16x16x32_bf16 v[14:17], v[140:143], v[208:211], 0
	v_mfma_f32_16x16x32_bf16 v[10:13], v[148:151], v[208:211], 0
	v_mfma_f32_16x16x32_bf16 v[62:65], v[144:147], v[176:179], v[62:65]
	v_mfma_f32_16x16x32_bf16 v[58:61], v[152:155], v[176:179], v[58:61]
	v_mfma_f32_16x16x32_bf16 v[46:49], v[144:147], v[184:187], v[46:49]
	v_mfma_f32_16x16x32_bf16 v[42:45], v[152:155], v[184:187], v[42:45]
	v_mfma_f32_16x16x32_bf16 v[30:33], v[144:147], v[192:195], v[30:33]
	v_mfma_f32_16x16x32_bf16 v[26:29], v[152:155], v[192:195], v[26:29]
	v_mfma_f32_16x16x32_bf16 v[14:17], v[144:147], v[212:215], v[14:17]
	v_mfma_f32_16x16x32_bf16 v[10:13], v[152:155], v[212:215], v[10:13]
	s_setprio 0
	s_setprio 1
	v_mfma_f32_16x16x32_bf16 v[54:57], v[156:159], v[172:175], 0
	v_mfma_f32_16x16x32_bf16 v[50:53], v[164:167], v[172:175], 0
	v_mfma_f32_16x16x32_bf16 v[38:41], v[156:159], v[180:183], 0
	v_mfma_f32_16x16x32_bf16 v[34:37], v[164:167], v[180:183], 0
	v_mfma_f32_16x16x32_bf16 v[22:25], v[156:159], v[188:191], 0
	v_mfma_f32_16x16x32_bf16 v[18:21], v[164:167], v[188:191], 0
	v_mfma_f32_16x16x32_bf16 v[6:9], v[156:159], v[208:211], 0
	v_mfma_f32_16x16x32_bf16 v[2:5], v[164:167], v[208:211], 0
	v_mfma_f32_16x16x32_bf16 v[54:57], v[160:163], v[176:179], v[54:57]
	v_mfma_f32_16x16x32_bf16 v[50:53], v[168:171], v[176:179], v[50:53]
	v_mfma_f32_16x16x32_bf16 v[38:41], v[160:163], v[184:187], v[38:41]
	v_mfma_f32_16x16x32_bf16 v[34:37], v[168:171], v[184:187], v[34:37]
	v_mfma_f32_16x16x32_bf16 v[22:25], v[160:163], v[192:195], v[22:25]
	v_mfma_f32_16x16x32_bf16 v[18:21], v[168:171], v[192:195], v[18:21]
	v_mfma_f32_16x16x32_bf16 v[6:9], v[160:163], v[212:215], v[6:9]
	v_mfma_f32_16x16x32_bf16 v[2:5], v[168:171], v[212:215], v[2:5]
	s_setprio 0
	s_barrier
	s_add_i32 s56, 0, 0x18000
	s_add_i32 s57, 0, 0x1c000
	v_add_u32_e32 v152, s56, v232
	v_add_u32_e32 v168, s57, v232
	ds_read_b128 v[140:143], v152
	ds_read_b128 v[144:147], v152 offset:1024
	ds_read_b128 v[148:151], v152 offset:2048
	ds_read_b128 v[152:155], v152 offset:3072
	ds_read_b128 v[156:159], v168
	ds_read_b128 v[160:163], v168 offset:1024
	ds_read_b128 v[164:167], v168 offset:2048
	ds_read_b128 v[168:171], v168 offset:3072
	s_add_u32 s30, s30, s6
	s_addc_u32 s31, s31, 0
	s_mov_b32 m0, s33
	ds_read_b128 v[172:175], v236 offset:32768
	ds_read_b128 v[176:179], v236 offset:33792
	ds_read_b128 v[180:183], v236 offset:34816
	ds_read_b128 v[184:187], v236 offset:35840
	ds_read_b128 v[188:191], v236 offset:36864
	ds_read_b128 v[192:195], v236 offset:37888
	ds_read_b128 v[208:211], v236 offset:38912
	ds_read_b128 v[212:215], v236 offset:39936
	global_load_lds_dwordx4 v0, s[30:31]
	s_mov_b32 m0, s42
	s_nop 0
	global_load_lds_dwordx4 v94, s[30:31]
	s_waitcnt vmcnt(8)
	s_waitcnt lgkmcnt(0)
	s_barrier
	s_setprio 1
	s_waitcnt lgkmcnt(0)
	v_mfma_f32_16x16x32_bf16 v[130:133], v[140:143], v[172:175], v[130:133]
	v_mfma_f32_16x16x32_bf16 v[126:129], v[148:151], v[172:175], v[126:129]
	v_mfma_f32_16x16x32_bf16 v[114:117], v[140:143], v[180:183], v[114:117]
	v_mfma_f32_16x16x32_bf16 v[110:113], v[148:151], v[180:183], v[110:113]
	v_mfma_f32_16x16x32_bf16 v[98:101], v[140:143], v[188:191], v[98:101]
	v_mfma_f32_16x16x32_bf16 v[90:93], v[148:151], v[188:191], v[90:93]
	v_mfma_f32_16x16x32_bf16 v[78:81], v[140:143], v[208:211], v[78:81]
	v_mfma_f32_16x16x32_bf16 v[74:77], v[148:151], v[208:211], v[74:77]
	v_mfma_f32_16x16x32_bf16 v[130:133], v[144:147], v[176:179], v[130:133]
	v_mfma_f32_16x16x32_bf16 v[126:129], v[152:155], v[176:179], v[126:129]
	v_mfma_f32_16x16x32_bf16 v[114:117], v[144:147], v[184:187], v[114:117]
	v_mfma_f32_16x16x32_bf16 v[110:113], v[152:155], v[184:187], v[110:113]
	v_mfma_f32_16x16x32_bf16 v[98:101], v[144:147], v[192:195], v[98:101]
	v_mfma_f32_16x16x32_bf16 v[90:93], v[152:155], v[192:195], v[90:93]
	v_mfma_f32_16x16x32_bf16 v[78:81], v[144:147], v[212:215], v[78:81]
	v_mfma_f32_16x16x32_bf16 v[74:77], v[152:155], v[212:215], v[74:77]
	s_setprio 0
	s_setprio 1
	v_mfma_f32_16x16x32_bf16 v[122:125], v[156:159], v[172:175], v[122:125]
	v_mfma_f32_16x16x32_bf16 v[118:121], v[164:167], v[172:175], v[118:121]
	v_mfma_f32_16x16x32_bf16 v[106:109], v[156:159], v[180:183], v[106:109]
	v_mfma_f32_16x16x32_bf16 v[102:105], v[164:167], v[180:183], v[102:105]
	v_mfma_f32_16x16x32_bf16 v[86:89], v[156:159], v[188:191], v[86:89]
	v_mfma_f32_16x16x32_bf16 v[82:85], v[164:167], v[188:191], v[82:85]
	v_mfma_f32_16x16x32_bf16 v[70:73], v[156:159], v[208:211], v[70:73]
	v_mfma_f32_16x16x32_bf16 v[66:69], v[164:167], v[208:211], v[66:69]
	v_mfma_f32_16x16x32_bf16 v[122:125], v[160:163], v[176:179], v[122:125]
	v_mfma_f32_16x16x32_bf16 v[118:121], v[168:171], v[176:179], v[118:121]
	v_mfma_f32_16x16x32_bf16 v[106:109], v[160:163], v[184:187], v[106:109]
	v_mfma_f32_16x16x32_bf16 v[102:105], v[168:171], v[184:187], v[102:105]
	v_mfma_f32_16x16x32_bf16 v[86:89], v[160:163], v[192:195], v[86:89]
	v_mfma_f32_16x16x32_bf16 v[82:85], v[168:171], v[192:195], v[82:85]
	v_mfma_f32_16x16x32_bf16 v[70:73], v[160:163], v[212:215], v[70:73]
	v_mfma_f32_16x16x32_bf16 v[66:69], v[168:171], v[212:215], v[66:69]
	s_setprio 0
	s_barrier
	s_add_i32 s71, s56, s25
	s_sub_u32 s54, s54, s6
	s_subb_u32 s55, s55, 0
	s_add_u32 s54, s54, 0x80
	s_addc_u32 s55, s55, 0
	s_mov_b32 m0, s71
	ds_read_b128 v[172:175], v236 offset:49152
	ds_read_b128 v[176:179], v236 offset:50176
	ds_read_b128 v[180:183], v236 offset:51200
	ds_read_b128 v[184:187], v236 offset:52224
	ds_read_b128 v[188:191], v236 offset:53248
	ds_read_b128 v[192:195], v236 offset:54272
	ds_read_b128 v[208:211], v236 offset:55296
	ds_read_b128 v[212:215], v236 offset:56320
	global_load_lds_dwordx4 v0, s[54:55]
	s_add_i32 m0, s71, 0x2000
	s_nop 0
	global_load_lds_dwordx4 v94, s[54:55]
	s_add_i32 s71, s57, s25
	s_add_u32 s54, s54, s6
	s_addc_u32 s55, s55, 0
	s_mov_b32 m0, s71
	s_nop 0
	global_load_lds_dwordx4 v0, s[54:55]
	s_add_i32 m0, s71, 0x2000
	s_nop 0
	global_load_lds_dwordx4 v94, s[54:55]
	s_sub_u32 s30, s30, s6
	s_subb_u32 s31, s31, 0
	s_add_u32 s30, s30, 0x80
	s_addc_u32 s31, s31, 0
	s_mov_b32 m0, s43
	s_nop 0
	global_load_lds_dwordx4 v0, s[30:31]
	s_mov_b32 m0, s44
	s_nop 0
	global_load_lds_dwordx4 v94, s[30:31]
	s_waitcnt vmcnt(8)
	s_waitcnt lgkmcnt(0)
	s_barrier
	s_setprio 1
	s_waitcnt lgkmcnt(0)
	v_mfma_f32_16x16x32_bf16 v[62:65], v[140:143], v[172:175], v[62:65]
	v_mfma_f32_16x16x32_bf16 v[58:61], v[148:151], v[172:175], v[58:61]
	v_mfma_f32_16x16x32_bf16 v[46:49], v[140:143], v[180:183], v[46:49]
	v_mfma_f32_16x16x32_bf16 v[42:45], v[148:151], v[180:183], v[42:45]
	v_mfma_f32_16x16x32_bf16 v[30:33], v[140:143], v[188:191], v[30:33]
	v_mfma_f32_16x16x32_bf16 v[26:29], v[148:151], v[188:191], v[26:29]
	v_mfma_f32_16x16x32_bf16 v[14:17], v[140:143], v[208:211], v[14:17]
	v_mfma_f32_16x16x32_bf16 v[10:13], v[148:151], v[208:211], v[10:13]
	v_mfma_f32_16x16x32_bf16 v[62:65], v[144:147], v[176:179], v[62:65]
	v_mfma_f32_16x16x32_bf16 v[58:61], v[152:155], v[176:179], v[58:61]
	v_mfma_f32_16x16x32_bf16 v[46:49], v[144:147], v[184:187], v[46:49]
	v_mfma_f32_16x16x32_bf16 v[42:45], v[152:155], v[184:187], v[42:45]
	v_mfma_f32_16x16x32_bf16 v[30:33], v[144:147], v[192:195], v[30:33]
	v_mfma_f32_16x16x32_bf16 v[26:29], v[152:155], v[192:195], v[26:29]
	v_mfma_f32_16x16x32_bf16 v[14:17], v[144:147], v[212:215], v[14:17]
	v_mfma_f32_16x16x32_bf16 v[10:13], v[152:155], v[212:215], v[10:13]
	s_setprio 0
	s_setprio 1
	v_mfma_f32_16x16x32_bf16 v[54:57], v[156:159], v[172:175], v[54:57]
	v_mfma_f32_16x16x32_bf16 v[50:53], v[164:167], v[172:175], v[50:53]
	v_mfma_f32_16x16x32_bf16 v[38:41], v[156:159], v[180:183], v[38:41]
	v_mfma_f32_16x16x32_bf16 v[34:37], v[164:167], v[180:183], v[34:37]
	v_mfma_f32_16x16x32_bf16 v[22:25], v[156:159], v[188:191], v[22:25]
	v_mfma_f32_16x16x32_bf16 v[18:21], v[164:167], v[188:191], v[18:21]
	v_mfma_f32_16x16x32_bf16 v[6:9], v[156:159], v[208:211], v[6:9]
	v_mfma_f32_16x16x32_bf16 v[2:5], v[164:167], v[208:211], v[2:5]
	v_mfma_f32_16x16x32_bf16 v[54:57], v[160:163], v[176:179], v[54:57]
	v_mfma_f32_16x16x32_bf16 v[50:53], v[168:171], v[176:179], v[50:53]
	v_mfma_f32_16x16x32_bf16 v[38:41], v[160:163], v[184:187], v[38:41]
	v_mfma_f32_16x16x32_bf16 v[34:37], v[168:171], v[184:187], v[34:37]
	v_mfma_f32_16x16x32_bf16 v[22:25], v[160:163], v[192:195], v[22:25]
	v_mfma_f32_16x16x32_bf16 v[18:21], v[168:171], v[192:195], v[18:21]
	v_mfma_f32_16x16x32_bf16 v[6:9], v[160:163], v[212:215], v[6:9]
	v_mfma_f32_16x16x32_bf16 v[2:5], v[168:171], v[212:215], v[2:5]
	s_setprio 0
	s_barrier
	s_add_u32 s51, s51, 0x100
	s_addc_u32 s52, s52, 0
	s_add_u32 s22, s22, 0x100
	s_addc_u32 s23, s23, 0
	s_mov_b32 s30, s53

.LBB0_564:
	s_ashr_i32 s21, s20, 31
	s_lshl_b64 s[22:23], s[20:21], 19
	s_add_u32 s22, s14, s22
	s_addc_u32 s23, s15, s23
	s_and_b64 s[30:31], s[36:37], exec
	s_cselect_b32 s21, s23, s41
	s_cselect_b32 s47, s22, s40
	s_ashr_i32 s19, s18, 31
	s_lshl_b64 s[30:31], s[18:19], 19
	s_add_u32 s30, s2, s30
	s_addc_u32 s31, s3, s31
	s_and_b64 s[42:43], s[36:37], exec
	s_cselect_b32 s19, s31, s39
	s_cselect_b32 s48, s30, s38
	s_add_u32 s49, s38, 0x100
	s_addc_u32 s50, s39, 0
	s_add_u32 s38, s40, 0x40080
	s_addc_u32 s39, s41, 0
	s_mov_b32 s51, -2
	s_add_u32 s40, s38, 0xfffc0080
	s_addc_u32 s41, s39, -1
	s_add_i32 s52, 0, 0x10000
	s_cmp_eq_u32 s51, 12
	s_cselect_b32 s43, s21, s41
	s_cselect_b32 s42, s47, s40
	v_add_u32_e32 v0, s52, v141
	s_cselect_b32 s41, s19, s50
	s_cselect_b32 s40, s48, s49
	s_add_i32 s54, 0, 0x14000
	ds_read_b128 v[146:149], v0
	ds_read_b128 v[150:153], v0 offset:1024
	ds_read_b128 v[154:157], v0 offset:2048
	ds_read_b128 v[158:161], v0 offset:3072
	v_add_u32_e32 v0, s54, v141
	ds_read_b128 v[162:165], v0
	ds_read_b128 v[166:169], v0 offset:1024
	ds_read_b128 v[170:173], v0 offset:2048
	ds_read_b128 v[174:177], v0 offset:3072
	s_add_i32 m0, s8, 0xc000
	ds_read_b128 v[178:181], v145
	ds_read_b128 v[182:185], v145 offset:1024
	ds_read_b128 v[186:189], v145 offset:2048
	ds_read_b128 v[190:193], v145 offset:3072
	ds_read_b128 v[194:197], v145 offset:4096
	ds_read_b128 v[208:211], v145 offset:5120
	ds_read_b128 v[212:215], v145 offset:6144
	ds_read_b128 v[216:219], v145 offset:7168
	global_load_lds_dwordx4 v138, s[38:39]
	s_add_i32 m0, s8, 0xe000
	s_nop 0
	global_load_lds_dwordx4 v136, s[38:39]
	s_waitcnt vmcnt(8)
	s_waitcnt lgkmcnt(0)
	s_barrier
	s_setprio 1
	s_waitcnt lgkmcnt(0)
	v_mfma_f32_16x16x32_bf16 v[130:133], v[146:149], v[178:181], 0
	v_mfma_f32_16x16x32_bf16 v[126:129], v[154:157], v[178:181], 0
	v_mfma_f32_16x16x32_bf16 v[114:117], v[146:149], v[186:189], 0
	v_mfma_f32_16x16x32_bf16 v[110:113], v[154:157], v[186:189], 0
	v_mfma_f32_16x16x32_bf16 v[98:101], v[146:149], v[194:197], 0
	v_mfma_f32_16x16x32_bf16 v[90:93], v[154:157], v[194:197], 0
	v_mfma_f32_16x16x32_bf16 v[78:81], v[146:149], v[212:215], 0
	v_mfma_f32_16x16x32_bf16 v[74:77], v[154:157], v[212:215], 0
	v_mfma_f32_16x16x32_bf16 v[130:133], v[150:153], v[182:185], v[130:133]
	v_mfma_f32_16x16x32_bf16 v[126:129], v[158:161], v[182:185], v[126:129]
	v_mfma_f32_16x16x32_bf16 v[114:117], v[150:153], v[190:193], v[114:117]
	v_mfma_f32_16x16x32_bf16 v[110:113], v[158:161], v[190:193], v[110:113]
	v_mfma_f32_16x16x32_bf16 v[98:101], v[150:153], v[208:211], v[98:101]
	v_mfma_f32_16x16x32_bf16 v[90:93], v[158:161], v[208:211], v[90:93]
	v_mfma_f32_16x16x32_bf16 v[78:81], v[150:153], v[216:219], v[78:81]
	v_mfma_f32_16x16x32_bf16 v[74:77], v[158:161], v[216:219], v[74:77]
	s_setprio 0
	s_setprio 1
	v_mfma_f32_16x16x32_bf16 v[122:125], v[162:165], v[178:181], 0
	v_mfma_f32_16x16x32_bf16 v[118:121], v[170:173], v[178:181], 0
	v_mfma_f32_16x16x32_bf16 v[106:109], v[162:165], v[186:189], 0
	v_mfma_f32_16x16x32_bf16 v[102:105], v[170:173], v[186:189], 0
	v_mfma_f32_16x16x32_bf16 v[86:89], v[162:165], v[194:197], 0
	v_mfma_f32_16x16x32_bf16 v[82:85], v[170:173], v[194:197], 0
	v_mfma_f32_16x16x32_bf16 v[70:73], v[162:165], v[212:215], 0
	v_mfma_f32_16x16x32_bf16 v[66:69], v[170:173], v[212:215], 0
	v_mfma_f32_16x16x32_bf16 v[122:125], v[166:169], v[182:185], v[122:125]
	v_mfma_f32_16x16x32_bf16 v[118:121], v[174:177], v[182:185], v[118:121]
	v_mfma_f32_16x16x32_bf16 v[106:109], v[166:169], v[190:193], v[106:109]
	v_mfma_f32_16x16x32_bf16 v[102:105], v[174:177], v[190:193], v[102:105]
	v_mfma_f32_16x16x32_bf16 v[86:89], v[166:169], v[208:211], v[86:89]
	v_mfma_f32_16x16x32_bf16 v[82:85], v[174:177], v[208:211], v[82:85]
	v_mfma_f32_16x16x32_bf16 v[70:73], v[166:169], v[216:219], v[70:73]
	v_mfma_f32_16x16x32_bf16 v[66:69], v[174:177], v[216:219], v[66:69]
	s_setprio 0
	s_barrier
	s_add_i32 s52, s52, s6
	s_mov_b32 m0, s52
	ds_read_b128 v[178:181], v145 offset:16384
	ds_read_b128 v[182:185], v145 offset:17408
	ds_read_b128 v[186:189], v145 offset:18432
	ds_read_b128 v[190:193], v145 offset:19456
	ds_read_b128 v[194:197], v145 offset:20480
	ds_read_b128 v[208:211], v145 offset:21504
	ds_read_b128 v[212:215], v145 offset:22528
	ds_read_b128 v[216:219], v145 offset:23552
	global_load_lds_dwordx4 v134, s[40:41]
	s_add_i32 m0, s52, 0x2000
	s_add_u32 s52, s40, 0x40000
	s_addc_u32 s53, s41, 0
	s_add_i32 s54, s54, s6
	global_load_lds_dwordx4 v94, s[40:41]
	s_mov_b32 m0, s54
	s_nop 0
	global_load_lds_dwordx4 v134, s[52:53]
	s_add_i32 m0, s54, 0x2000
	s_nop 0
	global_load_lds_dwordx4 v94, s[52:53]
	s_mov_b32 m0, s8
	s_nop 0
	global_load_lds_dwordx4 v134, s[42:43]
	s_mov_b32 m0, s9
	s_nop 0
	global_load_lds_dwordx4 v94, s[42:43]
	s_waitcnt vmcnt(8)
	s_waitcnt lgkmcnt(0)
	s_barrier
	s_setprio 1
	s_waitcnt lgkmcnt(0)
	v_mfma_f32_16x16x32_bf16 v[62:65], v[146:149], v[178:181], 0
	v_mfma_f32_16x16x32_bf16 v[58:61], v[154:157], v[178:181], 0
	v_mfma_f32_16x16x32_bf16 v[46:49], v[146:149], v[186:189], 0
	v_mfma_f32_16x16x32_bf16 v[42:45], v[154:157], v[186:189], 0
	v_mfma_f32_16x16x32_bf16 v[30:33], v[146:149], v[194:197], 0
	v_mfma_f32_16x16x32_bf16 v[26:29], v[154:157], v[194:197], 0
	v_mfma_f32_16x16x32_bf16 v[14:17], v[146:149], v[212:215], 0
	v_mfma_f32_16x16x32_bf16 v[10:13], v[154:157], v[212:215], 0
	v_mfma_f32_16x16x32_bf16 v[62:65], v[150:153], v[182:185], v[62:65]
	v_mfma_f32_16x16x32_bf16 v[58:61], v[158:161], v[182:185], v[58:61]
	v_mfma_f32_16x16x32_bf16 v[46:49], v[150:153], v[190:193], v[46:49]
	v_mfma_f32_16x16x32_bf16 v[42:45], v[158:161], v[190:193], v[42:45]
	v_mfma_f32_16x16x32_bf16 v[30:33], v[150:153], v[208:211], v[30:33]
	v_mfma_f32_16x16x32_bf16 v[26:29], v[158:161], v[208:211], v[26:29]
	v_mfma_f32_16x16x32_bf16 v[14:17], v[150:153], v[216:219], v[14:17]
	v_mfma_f32_16x16x32_bf16 v[10:13], v[158:161], v[216:219], v[10:13]
	s_setprio 0
	s_setprio 1
	v_mfma_f32_16x16x32_bf16 v[54:57], v[162:165], v[178:181], 0
	v_mfma_f32_16x16x32_bf16 v[50:53], v[170:173], v[178:181], 0
	v_mfma_f32_16x16x32_bf16 v[38:41], v[162:165], v[186:189], 0
	v_mfma_f32_16x16x32_bf16 v[34:37], v[170:173], v[186:189], 0
	v_mfma_f32_16x16x32_bf16 v[22:25], v[162:165], v[194:197], 0
	v_mfma_f32_16x16x32_bf16 v[18:21], v[170:173], v[194:197], 0
	v_mfma_f32_16x16x32_bf16 v[6:9], v[162:165], v[212:215], 0
	v_mfma_f32_16x16x32_bf16 v[2:5], v[170:173], v[212:215], 0
	v_mfma_f32_16x16x32_bf16 v[54:57], v[166:169], v[182:185], v[54:57]
	v_mfma_f32_16x16x32_bf16 v[50:53], v[174:177], v[182:185], v[50:53]
	v_mfma_f32_16x16x32_bf16 v[38:41], v[166:169], v[190:193], v[38:41]
	v_mfma_f32_16x16x32_bf16 v[34:37], v[174:177], v[190:193], v[34:37]
	v_mfma_f32_16x16x32_bf16 v[22:25], v[166:169], v[208:211], v[22:25]
	v_mfma_f32_16x16x32_bf16 v[18:21], v[174:177], v[208:211], v[18:21]
	v_mfma_f32_16x16x32_bf16 v[6:9], v[166:169], v[216:219], v[6:9]
	v_mfma_f32_16x16x32_bf16 v[2:5], v[174:177], v[216:219], v[2:5]
	s_setprio 0
	s_barrier
	s_add_i32 s52, 0, 0x18000
	v_add_u32_e32 v0, s52, v141
	s_add_i32 s53, 0, 0x1c000
	ds_read_b128 v[146:149], v0
	ds_read_b128 v[150:153], v0 offset:1024
	ds_read_b128 v[154:157], v0 offset:2048
	ds_read_b128 v[158:161], v0 offset:3072
	v_add_u32_e32 v0, s53, v141
	ds_read_b128 v[162:165], v0
	ds_read_b128 v[166:169], v0 offset:1024
	ds_read_b128 v[170:173], v0 offset:2048
	ds_read_b128 v[174:177], v0 offset:3072
	s_add_u32 s42, s42, 0x40000
	s_addc_u32 s43, s43, 0
	s_mov_b32 m0, s12
	ds_read_b128 v[178:181], v145 offset:32768
	ds_read_b128 v[182:185], v145 offset:33792
	ds_read_b128 v[186:189], v145 offset:34816
	ds_read_b128 v[190:193], v145 offset:35840
	ds_read_b128 v[194:197], v145 offset:36864
	ds_read_b128 v[208:211], v145 offset:37888
	ds_read_b128 v[212:215], v145 offset:38912
	ds_read_b128 v[216:219], v145 offset:39936
	global_load_lds_dwordx4 v134, s[42:43]
	s_mov_b32 m0, s13
	s_nop 0
	global_load_lds_dwordx4 v94, s[42:43]
	s_waitcnt vmcnt(8)
	s_waitcnt lgkmcnt(0)
	s_barrier
	s_setprio 1
	s_waitcnt lgkmcnt(0)
	v_mfma_f32_16x16x32_bf16 v[130:133], v[146:149], v[178:181], v[130:133]
	v_mfma_f32_16x16x32_bf16 v[126:129], v[154:157], v[178:181], v[126:129]
	v_mfma_f32_16x16x32_bf16 v[114:117], v[146:149], v[186:189], v[114:117]
	v_mfma_f32_16x16x32_bf16 v[110:113], v[154:157], v[186:189], v[110:113]
	v_mfma_f32_16x16x32_bf16 v[98:101], v[146:149], v[194:197], v[98:101]
	v_mfma_f32_16x16x32_bf16 v[90:93], v[154:157], v[194:197], v[90:93]
	v_mfma_f32_16x16x32_bf16 v[78:81], v[146:149], v[212:215], v[78:81]
	v_mfma_f32_16x16x32_bf16 v[74:77], v[154:157], v[212:215], v[74:77]
	v_mfma_f32_16x16x32_bf16 v[130:133], v[150:153], v[182:185], v[130:133]
	v_mfma_f32_16x16x32_bf16 v[126:129], v[158:161], v[182:185], v[126:129]
	v_mfma_f32_16x16x32_bf16 v[114:117], v[150:153], v[190:193], v[114:117]
	v_mfma_f32_16x16x32_bf16 v[110:113], v[158:161], v[190:193], v[110:113]
	v_mfma_f32_16x16x32_bf16 v[98:101], v[150:153], v[208:211], v[98:101]
	v_mfma_f32_16x16x32_bf16 v[90:93], v[158:161], v[208:211], v[90:93]
	v_mfma_f32_16x16x32_bf16 v[78:81], v[150:153], v[216:219], v[78:81]
	v_mfma_f32_16x16x32_bf16 v[74:77], v[158:161], v[216:219], v[74:77]
	s_setprio 0
	s_setprio 1
	v_mfma_f32_16x16x32_bf16 v[122:125], v[162:165], v[178:181], v[122:125]
	v_mfma_f32_16x16x32_bf16 v[118:121], v[170:173], v[178:181], v[118:121]
	v_mfma_f32_16x16x32_bf16 v[106:109], v[162:165], v[186:189], v[106:109]
	v_mfma_f32_16x16x32_bf16 v[102:105], v[170:173], v[186:189], v[102:105]
	v_mfma_f32_16x16x32_bf16 v[86:89], v[162:165], v[194:197], v[86:89]
	v_mfma_f32_16x16x32_bf16 v[82:85], v[170:173], v[194:197], v[82:85]
	v_mfma_f32_16x16x32_bf16 v[70:73], v[162:165], v[212:215], v[70:73]
	v_mfma_f32_16x16x32_bf16 v[66:69], v[170:173], v[212:215], v[66:69]
	v_mfma_f32_16x16x32_bf16 v[122:125], v[166:169], v[182:185], v[122:125]
	v_mfma_f32_16x16x32_bf16 v[118:121], v[174:177], v[182:185], v[118:121]
	v_mfma_f32_16x16x32_bf16 v[106:109], v[166:169], v[190:193], v[106:109]
	v_mfma_f32_16x16x32_bf16 v[102:105], v[174:177], v[190:193], v[102:105]
	v_mfma_f32_16x16x32_bf16 v[86:89], v[166:169], v[208:211], v[86:89]
	v_mfma_f32_16x16x32_bf16 v[82:85], v[174:177], v[208:211], v[82:85]
	v_mfma_f32_16x16x32_bf16 v[70:73], v[166:169], v[216:219], v[70:73]
	v_mfma_f32_16x16x32_bf16 v[66:69], v[174:177], v[216:219], v[66:69]
	s_setprio 0
	s_barrier
	s_add_i32 s54, s52, s6
	s_add_i32 m0, s54, 0xffffff80
	ds_read_b128 v[178:181], v145 offset:49152
	ds_read_b128 v[182:185], v145 offset:50176
	ds_read_b128 v[186:189], v145 offset:51200
	ds_read_b128 v[190:193], v145 offset:52224
	ds_read_b128 v[194:197], v145 offset:53248
	ds_read_b128 v[208:211], v145 offset:54272
	ds_read_b128 v[212:215], v145 offset:55296
	ds_read_b128 v[216:219], v145 offset:56320
	global_load_lds_dwordx4 v134, s[40:41] offset:128
	s_add_i32 m0, s54, 0x1f80
	s_nop 0
	global_load_lds_dwordx4 v94, s[40:41] offset:128
	s_add_i32 s54, s53, s6
	s_add_u32 s40, s40, 0x40080
	s_addc_u32 s41, s41, 0
	s_mov_b32 m0, s54
	s_nop 0
	global_load_lds_dwordx4 v134, s[40:41]
	s_add_i32 m0, s54, 0x2000
	s_nop 0
	global_load_lds_dwordx4 v94, s[40:41]
	s_add_u32 s42, s42, 0xfffc0080
	s_addc_u32 s43, s43, -1
	s_mov_b32 m0, s28
	s_nop 0
	global_load_lds_dwordx4 v134, s[42:43]
	s_mov_b32 m0, s29
	s_nop 0
	global_load_lds_dwordx4 v94, s[42:43]
	s_waitcnt vmcnt(8)
	s_waitcnt lgkmcnt(0)
	s_barrier
	s_setprio 1
	s_waitcnt lgkmcnt(0)
	v_mfma_f32_16x16x32_bf16 v[62:65], v[146:149], v[178:181], v[62:65]
	v_mfma_f32_16x16x32_bf16 v[58:61], v[154:157], v[178:181], v[58:61]
	v_mfma_f32_16x16x32_bf16 v[46:49], v[146:149], v[186:189], v[46:49]
	v_mfma_f32_16x16x32_bf16 v[42:45], v[154:157], v[186:189], v[42:45]
	v_mfma_f32_16x16x32_bf16 v[30:33], v[146:149], v[194:197], v[30:33]
	v_mfma_f32_16x16x32_bf16 v[26:29], v[154:157], v[194:197], v[26:29]
	v_mfma_f32_16x16x32_bf16 v[14:17], v[146:149], v[212:215], v[14:17]
	v_mfma_f32_16x16x32_bf16 v[10:13], v[154:157], v[212:215], v[10:13]
	v_mfma_f32_16x16x32_bf16 v[62:65], v[150:153], v[182:185], v[62:65]
	v_mfma_f32_16x16x32_bf16 v[58:61], v[158:161], v[182:185], v[58:61]
	v_mfma_f32_16x16x32_bf16 v[46:49], v[150:153], v[190:193], v[46:49]
	v_mfma_f32_16x16x32_bf16 v[42:45], v[158:161], v[190:193], v[42:45]
	v_mfma_f32_16x16x32_bf16 v[30:33], v[150:153], v[208:211], v[30:33]
	v_mfma_f32_16x16x32_bf16 v[26:29], v[158:161], v[208:211], v[26:29]
	v_mfma_f32_16x16x32_bf16 v[14:17], v[150:153], v[216:219], v[14:17]
	v_mfma_f32_16x16x32_bf16 v[10:13], v[158:161], v[216:219], v[10:13]
	s_setprio 0
	s_setprio 1
	v_mfma_f32_16x16x32_bf16 v[54:57], v[162:165], v[178:181], v[54:57]
	v_mfma_f32_16x16x32_bf16 v[50:53], v[170:173], v[178:181], v[50:53]
	v_mfma_f32_16x16x32_bf16 v[38:41], v[162:165], v[186:189], v[38:41]
	v_mfma_f32_16x16x32_bf16 v[34:37], v[170:173], v[186:189], v[34:37]
	v_mfma_f32_16x16x32_bf16 v[22:25], v[162:165], v[194:197], v[22:25]
	v_mfma_f32_16x16x32_bf16 v[18:21], v[170:173], v[194:197], v[18:21]
	v_mfma_f32_16x16x32_bf16 v[6:9], v[162:165], v[212:215], v[6:9]
	v_mfma_f32_16x16x32_bf16 v[2:5], v[170:173], v[212:215], v[2:5]
	v_mfma_f32_16x16x32_bf16 v[54:57], v[166:169], v[182:185], v[54:57]
	v_mfma_f32_16x16x32_bf16 v[50:53], v[174:177], v[182:185], v[50:53]
	v_mfma_f32_16x16x32_bf16 v[38:41], v[166:169], v[190:193], v[38:41]
	v_mfma_f32_16x16x32_bf16 v[34:37], v[174:177], v[190:193], v[34:37]
	v_mfma_f32_16x16x32_bf16 v[22:25], v[166:169], v[208:211], v[22:25]
	v_mfma_f32_16x16x32_bf16 v[18:21], v[174:177], v[208:211], v[18:21]
	v_mfma_f32_16x16x32_bf16 v[6:9], v[166:169], v[216:219], v[6:9]
	v_mfma_f32_16x16x32_bf16 v[2:5], v[174:177], v[216:219], v[2:5]
	s_setprio 0
	s_barrier
	s_add_i32 s51, s51, 2
	s_add_u32 s49, s49, 0x100
	s_addc_u32 s50, s50, 0
	s_add_u32 s38, s38, 0x100
	s_addc_u32 s39, s39, 0
